# attention tile loop: half-dead v_pk_add_f32 horizontal adds replaced by single v_add_f32 (7 fewer VALU issue slots per tile), same values
# speedup vs baseline: 1.1065x; 1.0005x over previous
.LBB0_1801:
	v_exp_f32_e32 v188, v66
	v_exp_f32_e32 v189, v50
	v_exp_f32_e32 v0, v67
	v_exp_f32_e32 v50, v51
	v_exp_f32_e32 v190, v52
	v_add_f32_e32 v51, v189, v188
	v_exp_f32_e32 v80, v80
	v_pk_add_f32 v[66:67], v[50:51], v[0:1]
	v_exp_f32_e32 v51, v68
	v_add_f32_e32 v67, v66, v67
	v_exp_f32_e32 v66, v69
	v_exp_f32_e32 v68, v53
	v_add_f32_e32 v69, v190, v51
	v_cvt_pk_bf16_f32 v50, v189, v50
	v_pk_add_f32 v[52:53], v[68:69], v[66:67]
	s_nop 0
	v_add_f32_e32 v179, v52, v53
	v_exp_f32_e32 v67, v70
	v_exp_f32_e32 v69, v54
	v_exp_f32_e32 v178, v71
	v_exp_f32_e32 v70, v55
	v_exp_f32_e32 v55, v72
	v_add_f32_e32 v71, v69, v67
	v_exp_f32_e32 v72, v57
	v_pk_add_f32 v[52:53], v[70:71], v[178:179]
	v_exp_f32_e32 v71, v56
	v_add_f32_e32 v181, v52, v53
	v_exp_f32_e32 v180, v73
	v_exp_f32_e32 v179, v58
	v_add_f32_e32 v73, v71, v55
	v_cvt_pk_bf16_f32 v54, v67, v178
	v_pk_add_f32 v[52:53], v[72:73], v[180:181]
	v_exp_f32_e32 v73, v74
	v_add_f32_e32 v183, v52, v53
	v_exp_f32_e32 v182, v75
	v_exp_f32_e32 v74, v59
	v_add_f32_e32 v75, v179, v73
	v_exp_f32_e32 v181, v60
	v_cvt_pk_bf16_f32 v55, v55, v180
	v_pk_add_f32 v[52:53], v[74:75], v[182:183]
	v_exp_f32_e32 v75, v76
	v_add_f32_e32 v185, v52, v53
	v_exp_f32_e32 v184, v77
	v_exp_f32_e32 v76, v61
	v_add_f32_e32 v77, v181, v75
	v_exp_f32_e32 v183, v62
	v_add3_u32 v62, s56, v208, v120
	v_pk_add_f32 v[52:53], v[76:77], v[184:185]
	v_exp_f32_e32 v77, v78
	v_add_f32_e32 v187, v52, v53
	v_cvt_pk_bf16_f32 v52, v188, v0
	v_add_u32_e32 v0, 0x3000, v62
	v_cvt_pk_bf16_f32 v53, v51, v66
	ds_read2_b64 v[56:59], v0 offset0:128 offset1:130
	v_exp_f32_e32 v186, v79
	v_exp_f32_e32 v66, v63
	v_add_f32_e32 v67, v183, v77
	s_waitcnt lgkmcnt(0)
	v_mfma_f32_32x32x16_bf16 v[18:33], v[52:55], v[56:59], v[18:33]
	v_add_f32_e64 v60, v66, v186
	v_add_f32_e64 v61, v67, v187
	v_add_u32_e32 v67, 0x4000, v62
	ds_read2_b64 v[56:59], v67 offset0:192 offset1:194
	v_add_f32_e64 v79, v60, v61
	v_exp_f32_e32 v78, v81
	ds_read2_b64 v[60:63], v0 offset0:132 offset1:134
	v_cvt_pk_bf16_f32 v51, v190, v68
	s_waitcnt lgkmcnt(1)
	v_mfma_f32_32x32x16_bf16 v[2:17], v[52:55], v[56:59], v[2:17]
	v_cvt_pk_bf16_f32 v52, v73, v182
	v_cvt_pk_bf16_f32 v53, v75, v184
	v_cvt_pk_bf16_f32 v54, v77, v186
	v_cvt_pk_bf16_f32 v55, v80, v78
	ds_read2_b64 v[56:59], v67 offset0:196 offset1:198
	s_waitcnt lgkmcnt(1)
	v_mfma_f32_32x32x16_bf16 v[18:33], v[52:55], v[60:63], v[18:33]
	s_waitcnt lgkmcnt(0)
	v_mfma_f32_32x32x16_bf16 v[2:17], v[52:55], v[56:59], v[2:17]
	v_cvt_pk_bf16_f32 v52, v69, v70
	v_cvt_pk_bf16_f32 v53, v71, v72
	ds_read2_b64 v[54:57], v0 offset0:136 offset1:138
	v_exp_f32_e32 v59, v64
	v_exp_f32_e32 v58, v65
	s_waitcnt lgkmcnt(0)
	v_mfma_f32_32x32x16_bf16 v[18:33], v[50:53], v[54:57], v[18:33]
	ds_read2_b64 v[54:57], v67 offset0:200 offset1:202
	s_waitcnt lgkmcnt(0)
	v_mfma_f32_32x32x16_bf16 v[2:17], v[50:53], v[54:57], v[2:17]
	v_cvt_pk_bf16_f32 v50, v179, v74
	v_cvt_pk_bf16_f32 v51, v181, v76
	v_cvt_pk_bf16_f32 v52, v183, v66
	v_cvt_pk_bf16_f32 v53, v59, v58
	ds_read2_b64 v[54:57], v0 offset0:140 offset1:142
	v_add_f32_e32 v59, v59, v80
	v_pk_add_f32 v[58:59], v[58:59], v[78:79]
	s_waitcnt lgkmcnt(0)
	v_mfma_f32_32x32x16_bf16 v[18:33], v[50:53], v[54:57], v[18:33]
	ds_read2_b64 v[54:57], v67 offset0:204 offset1:206
	v_add_f32_e32 v0, v58, v59
	v_add_f32_e32 v224, v224, v0
	s_waitcnt lgkmcnt(0)
	v_mfma_f32_32x32x16_bf16 v[2:17], v[50:53], v[54:57], v[2:17]
	s_andn2_b64 vcc, exec, s[8:9]
	s_cbranch_vccnz .LBB0_1790
